# SwiGLU K-loop only: B-fragment ds_reads of phases 2/5/6 issued inside the previous phase's MFMA block
# baseline (speedup 1.0000x reference)
.LBB0_923:
	ds_read_b128 v[162:165], v158
	ds_read_b128 v[166:169], v158 offset:1024
	ds_read_b128 v[170:173], v158 offset:2048
	ds_read_b128 v[174:177], v158 offset:3072
	v_add_u32_e32 v159, 0xc000, v151
	v_lshl_add_u64 v[182:183], s[6:7], 0, v[134:135]
	v_readfirstlane_b32 s2, v159
	v_lshl_add_u64 v[160:161], v[182:183], 0, s[96:97]
	s_mov_b32 m0, s2
	ds_read_b128 v[178:181], v146
	ds_read_b128 v[186:189], v146 offset:1024
	ds_read_b128 v[190:193], v145
	ds_read_b128 v[198:201], v145 offset:1024
	ds_read_b128 v[202:205], v144
	ds_read_b128 v[218:221], v144 offset:1024
	ds_read_b128 v[222:225], v143
	ds_read_b128 v[226:229], v143 offset:1024
	global_load_lds_dwordx4 v[160:161], off
	v_add_u32_e32 v160, 0xc000, v153
	v_lshl_add_u64 v[194:195], s[6:7], 0, v[132:133]
	v_readfirstlane_b32 s2, v160
	v_lshl_add_u64 v[196:197], v[194:195], 0, s[96:97]
	s_mov_b32 m0, s2
	s_nop 0
	global_load_lds_dwordx4 v[196:197], off
	s_waitcnt lgkmcnt(8)
	s_barrier
	s_waitcnt lgkmcnt(0)
	s_waitcnt lgkmcnt(0)
	v_mfma_f32_16x16x32_bf16 v[126:129], v[162:165], v[178:181], v[126:129]
	v_mfma_f32_16x16x32_bf16 v[122:125], v[170:173], v[178:181], v[122:125]
	ds_read_b128 v[230:233], v155
	v_mfma_f32_16x16x32_bf16 v[118:121], v[162:165], v[190:193], v[118:121]
	v_mfma_f32_16x16x32_bf16 v[114:117], v[170:173], v[190:193], v[114:117]
	v_mfma_f32_16x16x32_bf16 v[110:113], v[162:165], v[202:205], v[110:113]
	v_mfma_f32_16x16x32_bf16 v[106:109], v[170:173], v[202:205], v[106:109]
	ds_read_b128 v[234:237], v155 offset:1024
	v_mfma_f32_16x16x32_bf16 v[102:105], v[162:165], v[222:225], v[102:105]
	v_mfma_f32_16x16x32_bf16 v[98:101], v[170:173], v[222:225], v[98:101]
	v_mfma_f32_16x16x32_bf16 v[126:129], v[166:169], v[186:189], v[126:129]
	v_mfma_f32_16x16x32_bf16 v[122:125], v[174:177], v[186:189], v[122:125]
	ds_read_b128 v[238:241], v155 offset:2048
	v_mfma_f32_16x16x32_bf16 v[118:121], v[166:169], v[198:201], v[118:121]
	v_mfma_f32_16x16x32_bf16 v[114:117], v[174:177], v[198:201], v[114:117]
	v_mfma_f32_16x16x32_bf16 v[110:113], v[166:169], v[218:221], v[110:113]
	v_mfma_f32_16x16x32_bf16 v[106:109], v[174:177], v[218:221], v[106:109]
	ds_read_b128 v[242:245], v155 offset:3072
	v_mfma_f32_16x16x32_bf16 v[102:105], v[166:169], v[226:229], v[102:105]
	v_mfma_f32_16x16x32_bf16 v[98:101], v[174:177], v[226:229], v[98:101]
	s_barrier
	v_add_u32_e32 v161, s33, v141
	v_lshl_add_u64 v[196:197], s[6:7], 0, v[138:139]
	v_readfirstlane_b32 s2, v161
	v_lshl_add_u64 v[206:207], v[196:197], 0, s[78:79]
	s_mov_b32 m0, s2
	v_add_u32_e32 v161, s33, v142
	global_load_lds_dwordx4 v[206:207], off
	v_lshl_add_u64 v[206:207], s[6:7], 0, v[136:137]
	v_readfirstlane_b32 s2, v161
	v_lshl_add_u64 v[246:247], v[206:207], 0, s[78:79]
	s_mov_b32 m0, s2
	s_nop 0
	global_load_lds_dwordx4 v[246:247], off
	s_barrier
	s_waitcnt lgkmcnt(0)
	s_waitcnt lgkmcnt(0)
	v_mfma_f32_16x16x32_bf16 v[94:97], v[230:233], v[178:181], v[94:97]
	v_mfma_f32_16x16x32_bf16 v[90:93], v[238:241], v[178:181], v[90:93]
	v_mfma_f32_16x16x32_bf16 v[86:89], v[230:233], v[190:193], v[86:89]
	v_mfma_f32_16x16x32_bf16 v[82:85], v[238:241], v[190:193], v[82:85]
	v_mfma_f32_16x16x32_bf16 v[78:81], v[230:233], v[202:205], v[78:81]
	v_mfma_f32_16x16x32_bf16 v[74:77], v[238:241], v[202:205], v[74:77]
	v_mfma_f32_16x16x32_bf16 v[70:73], v[230:233], v[222:225], v[70:73]
	v_mfma_f32_16x16x32_bf16 v[66:69], v[238:241], v[222:225], v[66:69]
	v_mfma_f32_16x16x32_bf16 v[94:97], v[234:237], v[186:189], v[94:97]
	v_mfma_f32_16x16x32_bf16 v[90:93], v[242:245], v[186:189], v[90:93]
	v_mfma_f32_16x16x32_bf16 v[86:89], v[234:237], v[198:201], v[86:89]
	v_mfma_f32_16x16x32_bf16 v[82:85], v[242:245], v[198:201], v[82:85]
	v_mfma_f32_16x16x32_bf16 v[78:81], v[234:237], v[218:221], v[78:81]
	v_mfma_f32_16x16x32_bf16 v[74:77], v[242:245], v[218:221], v[74:77]
	v_mfma_f32_16x16x32_bf16 v[70:73], v[234:237], v[226:229], v[70:73]
	v_mfma_f32_16x16x32_bf16 v[66:69], v[242:245], v[226:229], v[66:69]
	v_readfirstlane_b32 s2, v151
	v_lshl_add_u64 v[246:247], v[182:183], 0, s[82:83]
	s_mov_b32 m0, s2
	v_readfirstlane_b32 s2, v153
	s_barrier
	ds_read_b128 v[178:181], v146 offset:16384
	ds_read_b128 v[186:189], v146 offset:17408
	ds_read_b128 v[190:193], v145 offset:16384
	ds_read_b128 v[198:201], v145 offset:17408
	ds_read_b128 v[202:205], v144 offset:16384
	ds_read_b128 v[218:221], v144 offset:17408
	ds_read_b128 v[222:225], v143 offset:16384
	ds_read_b128 v[226:229], v143 offset:17408
	global_load_lds_dwordx4 v[246:247], off
	v_lshl_add_u64 v[246:247], v[194:195], 0, s[82:83]
	s_mov_b32 m0, s2
	s_nop 0
	global_load_lds_dwordx4 v[246:247], off
	s_barrier
	s_waitcnt lgkmcnt(0)
	s_waitcnt lgkmcnt(0)
	v_mfma_f32_16x16x32_bf16 v[62:65], v[162:165], v[178:181], v[62:65]
	v_mfma_f32_16x16x32_bf16 v[58:61], v[170:173], v[178:181], v[58:61]
	v_mfma_f32_16x16x32_bf16 v[54:57], v[162:165], v[190:193], v[54:57]
	v_mfma_f32_16x16x32_bf16 v[50:53], v[170:173], v[190:193], v[50:53]
	v_mfma_f32_16x16x32_bf16 v[46:49], v[162:165], v[202:205], v[46:49]
	v_mfma_f32_16x16x32_bf16 v[42:45], v[170:173], v[202:205], v[42:45]
	v_mfma_f32_16x16x32_bf16 v[38:41], v[162:165], v[222:225], v[38:41]
	v_mfma_f32_16x16x32_bf16 v[34:37], v[170:173], v[222:225], v[34:37]
	v_mfma_f32_16x16x32_bf16 v[62:65], v[166:169], v[186:189], v[62:65]
	v_mfma_f32_16x16x32_bf16 v[58:61], v[174:177], v[186:189], v[58:61]
	v_mfma_f32_16x16x32_bf16 v[54:57], v[166:169], v[198:201], v[54:57]
	v_mfma_f32_16x16x32_bf16 v[50:53], v[174:177], v[198:201], v[50:53]
	v_mfma_f32_16x16x32_bf16 v[46:49], v[166:169], v[218:221], v[46:49]
	v_mfma_f32_16x16x32_bf16 v[42:45], v[174:177], v[218:221], v[42:45]
	v_mfma_f32_16x16x32_bf16 v[38:41], v[166:169], v[226:229], v[38:41]
	v_mfma_f32_16x16x32_bf16 v[34:37], v[174:177], v[226:229], v[34:37]
	s_barrier
	v_add_u32_e32 v161, s86, v141
	v_lshl_add_u64 v[162:163], v[196:197], 0, s[90:91]
	v_readfirstlane_b32 s2, v161
	v_add_u32_e32 v161, s86, v142
	s_mov_b32 m0, s2
	v_readfirstlane_b32 s2, v161
	global_load_lds_dwordx4 v[162:163], off
	v_lshl_add_u64 v[162:163], v[206:207], 0, s[90:91]
	s_mov_b32 m0, s2
	s_nop 0
	global_load_lds_dwordx4 v[162:163], off
	s_waitcnt vmcnt(6)
	s_barrier
	v_mfma_f32_16x16x32_bf16 v[30:33], v[230:233], v[178:181], v[30:33]
	v_mfma_f32_16x16x32_bf16 v[26:29], v[238:241], v[178:181], v[26:29]
	ds_read_b128 v[162:165], v148
	v_mfma_f32_16x16x32_bf16 v[22:25], v[230:233], v[190:193], v[22:25]
	v_mfma_f32_16x16x32_bf16 v[18:21], v[238:241], v[190:193], v[18:21]
	v_mfma_f32_16x16x32_bf16 v[14:17], v[230:233], v[202:205], v[14:17]
	v_mfma_f32_16x16x32_bf16 v[10:13], v[238:241], v[202:205], v[10:13]
	ds_read_b128 v[166:169], v148 offset:1024
	v_mfma_f32_16x16x32_bf16 v[6:9], v[230:233], v[222:225], v[6:9]
	v_mfma_f32_16x16x32_bf16 v[2:5], v[238:241], v[222:225], v[2:5]
	v_mfma_f32_16x16x32_bf16 v[30:33], v[234:237], v[186:189], v[30:33]
	v_mfma_f32_16x16x32_bf16 v[26:29], v[242:245], v[186:189], v[26:29]
	ds_read_b128 v[170:173], v148 offset:2048
	v_mfma_f32_16x16x32_bf16 v[22:25], v[234:237], v[198:201], v[22:25]
	v_mfma_f32_16x16x32_bf16 v[18:21], v[242:245], v[198:201], v[18:21]
	v_mfma_f32_16x16x32_bf16 v[14:17], v[234:237], v[218:221], v[14:17]
	v_mfma_f32_16x16x32_bf16 v[10:13], v[242:245], v[218:221], v[10:13]
	ds_read_b128 v[174:177], v148 offset:3072
	v_mfma_f32_16x16x32_bf16 v[6:9], v[234:237], v[226:229], v[6:9]
	v_mfma_f32_16x16x32_bf16 v[2:5], v[242:245], v[226:229], v[2:5]
	s_barrier
	v_add_u32_e32 v161, 0x4000, v151
	v_lshl_add_u64 v[230:231], v[182:183], 0, s[34:35]
	v_readfirstlane_b32 s2, v161
	v_add_u32_e32 v161, 0x4000, v153
	s_mov_b32 m0, s2
	v_readfirstlane_b32 s2, v161
	ds_read_b128 v[178:181], v146 offset:32768
	ds_read_b128 v[186:189], v146 offset:33792
	ds_read_b128 v[190:193], v145 offset:32768
	ds_read_b128 v[198:201], v145 offset:33792
	ds_read_b128 v[202:205], v144 offset:32768
	ds_read_b128 v[218:221], v144 offset:33792
	ds_read_b128 v[222:225], v143 offset:32768
	ds_read_b128 v[226:229], v143 offset:33792
	global_load_lds_dwordx4 v[230:231], off
	v_lshl_add_u64 v[230:231], v[194:195], 0, s[34:35]
	s_mov_b32 m0, s2
	s_nop 0
	global_load_lds_dwordx4 v[230:231], off
	s_waitcnt lgkmcnt(8)
	s_barrier
	s_waitcnt lgkmcnt(0)
	s_waitcnt lgkmcnt(0)
	v_mfma_f32_16x16x32_bf16 v[126:129], v[162:165], v[178:181], v[126:129]
	v_mfma_f32_16x16x32_bf16 v[122:125], v[170:173], v[178:181], v[122:125]
	ds_read_b128 v[230:233], v147
	v_mfma_f32_16x16x32_bf16 v[118:121], v[162:165], v[190:193], v[118:121]
	v_mfma_f32_16x16x32_bf16 v[114:117], v[170:173], v[190:193], v[114:117]
	v_mfma_f32_16x16x32_bf16 v[110:113], v[162:165], v[202:205], v[110:113]
	v_mfma_f32_16x16x32_bf16 v[106:109], v[170:173], v[202:205], v[106:109]
	ds_read_b128 v[234:237], v147 offset:1024
	v_mfma_f32_16x16x32_bf16 v[102:105], v[162:165], v[222:225], v[102:105]
	v_mfma_f32_16x16x32_bf16 v[98:101], v[170:173], v[222:225], v[98:101]
	v_mfma_f32_16x16x32_bf16 v[126:129], v[166:169], v[186:189], v[126:129]
	v_mfma_f32_16x16x32_bf16 v[122:125], v[174:177], v[186:189], v[122:125]
	ds_read_b128 v[238:241], v147 offset:2048
	v_mfma_f32_16x16x32_bf16 v[118:121], v[166:169], v[198:201], v[118:121]
	v_mfma_f32_16x16x32_bf16 v[114:117], v[174:177], v[198:201], v[114:117]
	v_mfma_f32_16x16x32_bf16 v[110:113], v[166:169], v[218:221], v[110:113]
	v_mfma_f32_16x16x32_bf16 v[106:109], v[174:177], v[218:221], v[106:109]
	ds_read_b128 v[242:245], v147 offset:3072
	v_mfma_f32_16x16x32_bf16 v[102:105], v[166:169], v[226:229], v[102:105]
	v_mfma_f32_16x16x32_bf16 v[98:101], v[174:177], v[226:229], v[98:101]
	s_barrier
	v_readfirstlane_b32 s2, v149
	v_lshl_add_u64 v[246:247], v[196:197], 0, s[92:93]
	s_mov_b32 m0, s2
	v_readfirstlane_b32 s2, v150
	global_load_lds_dwordx4 v[246:247], off
	v_lshl_add_u64 v[246:247], v[206:207], 0, s[92:93]
	s_mov_b32 m0, s2
	s_nop 0
	global_load_lds_dwordx4 v[246:247], off
	s_barrier
	s_waitcnt lgkmcnt(0)
	s_waitcnt lgkmcnt(0)
	v_mfma_f32_16x16x32_bf16 v[94:97], v[230:233], v[178:181], v[94:97]
	v_mfma_f32_16x16x32_bf16 v[90:93], v[238:241], v[178:181], v[90:93]
	v_mfma_f32_16x16x32_bf16 v[86:89], v[230:233], v[190:193], v[86:89]
	v_mfma_f32_16x16x32_bf16 v[82:85], v[238:241], v[190:193], v[82:85]
	v_mfma_f32_16x16x32_bf16 v[78:81], v[230:233], v[202:205], v[78:81]
	v_mfma_f32_16x16x32_bf16 v[74:77], v[238:241], v[202:205], v[74:77]
	v_mfma_f32_16x16x32_bf16 v[70:73], v[230:233], v[222:225], v[70:73]
	v_mfma_f32_16x16x32_bf16 v[66:69], v[238:241], v[222:225], v[66:69]
	v_mfma_f32_16x16x32_bf16 v[94:97], v[234:237], v[186:189], v[94:97]
	v_mfma_f32_16x16x32_bf16 v[90:93], v[242:245], v[186:189], v[90:93]
	v_mfma_f32_16x16x32_bf16 v[86:89], v[234:237], v[198:201], v[86:89]
	v_mfma_f32_16x16x32_bf16 v[82:85], v[242:245], v[198:201], v[82:85]
	v_mfma_f32_16x16x32_bf16 v[78:81], v[234:237], v[218:221], v[78:81]
	v_mfma_f32_16x16x32_bf16 v[74:77], v[242:245], v[218:221], v[74:77]
	v_mfma_f32_16x16x32_bf16 v[70:73], v[234:237], v[226:229], v[70:73]
	v_mfma_f32_16x16x32_bf16 v[66:69], v[242:245], v[226:229], v[66:69]
	v_readfirstlane_b32 s2, v152
	v_lshl_add_u64 v[182:183], v[182:183], 0, s[50:51]
	s_mov_b32 m0, s2
	v_readfirstlane_b32 s2, v154
	s_barrier
	ds_read_b128 v[178:181], v146 offset:49152
	ds_read_b128 v[186:189], v146 offset:50176
	ds_read_b128 v[190:193], v145 offset:49152
	ds_read_b128 v[198:201], v145 offset:50176
	ds_read_b128 v[202:205], v144 offset:49152
	ds_read_b128 v[218:221], v144 offset:50176
	ds_read_b128 v[222:225], v143 offset:49152
	ds_read_b128 v[226:229], v143 offset:50176
	global_load_lds_dwordx4 v[182:183], off
	v_lshl_add_u64 v[182:183], v[194:195], 0, s[50:51]
	s_mov_b32 m0, s2
	s_nop 0
	global_load_lds_dwordx4 v[182:183], off
	s_barrier
	s_waitcnt lgkmcnt(0)
	s_waitcnt lgkmcnt(0)
	v_mfma_f32_16x16x32_bf16 v[62:65], v[162:165], v[178:181], v[62:65]
	v_mfma_f32_16x16x32_bf16 v[58:61], v[170:173], v[178:181], v[58:61]
	v_mfma_f32_16x16x32_bf16 v[54:57], v[162:165], v[190:193], v[54:57]
	v_mfma_f32_16x16x32_bf16 v[50:53], v[170:173], v[190:193], v[50:53]
	v_mfma_f32_16x16x32_bf16 v[46:49], v[162:165], v[202:205], v[46:49]
	v_mfma_f32_16x16x32_bf16 v[42:45], v[170:173], v[202:205], v[42:45]
	v_mfma_f32_16x16x32_bf16 v[38:41], v[162:165], v[222:225], v[38:41]
	v_mfma_f32_16x16x32_bf16 v[34:37], v[170:173], v[222:225], v[34:37]
	v_mfma_f32_16x16x32_bf16 v[62:65], v[166:169], v[186:189], v[62:65]
	v_mfma_f32_16x16x32_bf16 v[58:61], v[174:177], v[186:189], v[58:61]
	v_mfma_f32_16x16x32_bf16 v[54:57], v[166:169], v[198:201], v[54:57]
	v_mfma_f32_16x16x32_bf16 v[50:53], v[174:177], v[198:201], v[50:53]
	v_mfma_f32_16x16x32_bf16 v[46:49], v[166:169], v[218:221], v[46:49]
	v_mfma_f32_16x16x32_bf16 v[42:45], v[174:177], v[218:221], v[42:45]
	v_mfma_f32_16x16x32_bf16 v[38:41], v[166:169], v[226:229], v[38:41]
	v_mfma_f32_16x16x32_bf16 v[34:37], v[174:177], v[226:229], v[34:37]
	s_barrier
	v_readfirstlane_b32 s2, v156
	v_lshl_add_u64 v[162:163], v[196:197], 0, s[4:5]
	s_mov_b32 m0, s2
	v_readfirstlane_b32 s2, v157
	global_load_lds_dwordx4 v[162:163], off
	v_lshl_add_u64 v[162:163], v[206:207], 0, s[4:5]
	s_mov_b32 m0, s2
	s_nop 0
	global_load_lds_dwordx4 v[162:163], off
	s_waitcnt vmcnt(6)
	s_barrier
	v_mfma_f32_16x16x32_bf16 v[30:33], v[230:233], v[178:181], v[30:33]
	v_mfma_f32_16x16x32_bf16 v[26:29], v[238:241], v[178:181], v[26:29]
	v_mfma_f32_16x16x32_bf16 v[22:25], v[230:233], v[190:193], v[22:25]
	v_mfma_f32_16x16x32_bf16 v[18:21], v[238:241], v[190:193], v[18:21]
	v_mfma_f32_16x16x32_bf16 v[14:17], v[230:233], v[202:205], v[14:17]
	v_mfma_f32_16x16x32_bf16 v[10:13], v[238:241], v[202:205], v[10:13]
	v_mfma_f32_16x16x32_bf16 v[6:9], v[230:233], v[222:225], v[6:9]
	v_mfma_f32_16x16x32_bf16 v[2:5], v[238:241], v[222:225], v[2:5]
	v_mfma_f32_16x16x32_bf16 v[30:33], v[234:237], v[186:189], v[30:33]
	v_mfma_f32_16x16x32_bf16 v[26:29], v[242:245], v[186:189], v[26:29]
	v_mfma_f32_16x16x32_bf16 v[22:25], v[234:237], v[198:201], v[22:25]
	v_mfma_f32_16x16x32_bf16 v[18:21], v[242:245], v[198:201], v[18:21]
	v_mfma_f32_16x16x32_bf16 v[14:17], v[234:237], v[218:221], v[14:17]
	v_mfma_f32_16x16x32_bf16 v[10:13], v[242:245], v[218:221], v[10:13]
	v_mfma_f32_16x16x32_bf16 v[6:9], v[234:237], v[226:229], v[6:9]
	v_mfma_f32_16x16x32_bf16 v[2:5], v[242:245], v[226:229], v[2:5]
	s_add_i32 s16, s16, 2
	v_lshl_add_u64 v[132:133], v[132:133], 0, s[36:37]
	v_lshl_add_u64 v[134:135], v[134:135], 0, s[36:37]
	v_lshl_add_u64 v[136:137], v[136:137], 0, s[36:37]
	s_cmp_gt_u32 s16, 11
	v_lshl_add_u64 v[138:139], v[138:139], 0, s[36:37]
	s_barrier
	s_cbranch_scc0 .LBB0_923
	s_or_b32 s2, s22, 0x80
	s_ashr_i32 s3, s2, 31
	s_lshl_b64 s[2:3], s[2:3], 11
	s_add_u32 s2, s30, s2
	s_addc_u32 s3, s31, s3
	v_readfirstlane_b32 s10, v159
	v_lshl_add_u64 v[156:157], s[2:3], 0, v[0:1]
	s_mov_b32 m0, s10
	v_lshl_add_u64 v[130:131], s[2:3], 0, v[130:131]
	v_readfirstlane_b32 s2, v160
	ds_read_b128 v[132:135], v158
	ds_read_b128 v[136:139], v158 offset:1024
	ds_read_b128 v[150:153], v158 offset:2048
	ds_read_b128 v[162:165], v158 offset:3072
	ds_read_b128 v[166:169], v146
	ds_read_b128 v[170:173], v146 offset:1024
	ds_read_b128 v[174:177], v145
	ds_read_b128 v[178:181], v145 offset:1024
	ds_read_b128 v[186:189], v144
	ds_read_b128 v[190:193], v144 offset:1024
	ds_read_b128 v[198:201], v143
	ds_read_b128 v[202:205], v143 offset:1024
	global_load_lds_dwordx4 v[156:157], off
	s_mov_b32 m0, s2
	s_nop 0
	global_load_lds_dwordx4 v[130:131], off
	s_barrier
	s_waitcnt lgkmcnt(0)
	s_waitcnt lgkmcnt(0)
	v_mfma_f32_16x16x32_bf16 v[126:129], v[132:135], v[166:169], v[126:129]
	v_mfma_f32_16x16x32_bf16 v[118:121], v[132:135], v[174:177], v[118:121]
	v_mfma_f32_16x16x32_bf16 v[110:113], v[132:135], v[186:189], v[110:113]
	v_mfma_f32_16x16x32_bf16 v[102:105], v[132:135], v[198:201], v[102:105]
	v_mfma_f32_16x16x32_bf16 v[126:129], v[136:139], v[170:173], v[126:129]
	v_mfma_f32_16x16x32_bf16 v[122:125], v[150:153], v[166:169], v[122:125]
	v_mfma_f32_16x16x32_bf16 v[118:121], v[136:139], v[178:181], v[118:121]
	v_mfma_f32_16x16x32_bf16 v[114:117], v[150:153], v[174:177], v[114:117]
	v_mfma_f32_16x16x32_bf16 v[110:113], v[136:139], v[190:193], v[110:113]
	v_mfma_f32_16x16x32_bf16 v[106:109], v[150:153], v[186:189], v[106:109]
	v_mfma_f32_16x16x32_bf16 v[102:105], v[136:139], v[202:205], v[102:105]
	v_mfma_f32_16x16x32_bf16 v[98:101], v[150:153], v[198:201], v[98:101]
	v_mfma_f32_16x16x32_bf16 v[156:159], v[162:165], v[170:173], v[122:125]
	v_mfma_f32_16x16x32_bf16 v[218:221], v[162:165], v[178:181], v[114:117]
	v_mfma_f32_16x16x32_bf16 v[222:225], v[162:165], v[190:193], v[106:109]
	v_mfma_f32_16x16x32_bf16 v[226:229], v[162:165], v[202:205], v[98:101]
	s_barrier
	s_nop 1
	ds_read_b128 v[98:101], v155
	ds_read_b128 v[106:109], v155 offset:1024
	ds_read_b128 v[114:117], v155 offset:2048
	ds_read_b128 v[122:125], v155 offset:3072
	s_barrier
	s_waitcnt lgkmcnt(0)
	s_waitcnt lgkmcnt(0)
	v_mfma_f32_16x16x32_bf16 v[94:97], v[98:101], v[166:169], v[94:97]
	v_mfma_f32_16x16x32_bf16 v[86:89], v[98:101], v[174:177], v[86:89]
	v_mfma_f32_16x16x32_bf16 v[78:81], v[98:101], v[186:189], v[78:81]
	v_mfma_f32_16x16x32_bf16 v[70:73], v[98:101], v[198:201], v[70:73]
	v_mfma_f32_16x16x32_bf16 v[94:97], v[106:109], v[170:173], v[94:97]
	v_mfma_f32_16x16x32_bf16 v[90:93], v[114:117], v[166:169], v[90:93]
	v_mfma_f32_16x16x32_bf16 v[86:89], v[106:109], v[178:181], v[86:89]
	v_mfma_f32_16x16x32_bf16 v[82:85], v[114:117], v[174:177], v[82:85]
	v_mfma_f32_16x16x32_bf16 v[78:81], v[106:109], v[190:193], v[78:81]
	v_mfma_f32_16x16x32_bf16 v[74:77], v[114:117], v[186:189], v[74:77]
	v_mfma_f32_16x16x32_bf16 v[70:73], v[106:109], v[202:205], v[70:73]
	v_mfma_f32_16x16x32_bf16 v[66:69], v[114:117], v[198:201], v[66:69]
	v_mfma_f32_16x16x32_bf16 v[166:169], v[122:125], v[170:173], v[90:93]
	v_mfma_f32_16x16x32_bf16 v[170:173], v[122:125], v[178:181], v[82:85]
	v_mfma_f32_16x16x32_bf16 v[174:177], v[122:125], v[190:193], v[74:77]
	v_mfma_f32_16x16x32_bf16 v[178:181], v[122:125], v[202:205], v[66:69]
	s_barrier
	s_nop 1
	ds_read_b128 v[66:69], v146 offset:16384
	ds_read_b128 v[74:77], v146 offset:17408
	ds_read_b128 v[82:85], v145 offset:16384
	ds_read_b128 v[90:93], v145 offset:17408
	ds_read_b128 v[186:189], v144 offset:16384
	ds_read_b128 v[190:193], v144 offset:17408
	ds_read_b128 v[198:201], v143 offset:16384
	ds_read_b128 v[202:205], v143 offset:17408
	s_waitcnt vmcnt(4)
	s_barrier
	s_waitcnt lgkmcnt(0)
	s_waitcnt lgkmcnt(0)
	v_mfma_f32_16x16x32_bf16 v[62:65], v[132:135], v[66:69], v[62:65]
	v_mfma_f32_16x16x32_bf16 v[54:57], v[132:135], v[82:85], v[54:57]
	v_mfma_f32_16x16x32_bf16 v[46:49], v[132:135], v[186:189], v[46:49]
	v_mfma_f32_16x16x32_bf16 v[38:41], v[132:135], v[198:201], v[38:41]
	v_mfma_f32_16x16x32_bf16 v[62:65], v[136:139], v[74:77], v[62:65]
	v_mfma_f32_16x16x32_bf16 v[58:61], v[150:153], v[66:69], v[58:61]
	v_mfma_f32_16x16x32_bf16 v[54:57], v[136:139], v[90:93], v[54:57]
	v_mfma_f32_16x16x32_bf16 v[50:53], v[150:153], v[82:85], v[50:53]
	v_mfma_f32_16x16x32_bf16 v[46:49], v[136:139], v[190:193], v[46:49]
	v_mfma_f32_16x16x32_bf16 v[42:45], v[150:153], v[186:189], v[42:45]
	v_mfma_f32_16x16x32_bf16 v[38:41], v[136:139], v[202:205], v[38:41]
	v_mfma_f32_16x16x32_bf16 v[34:37], v[150:153], v[198:201], v[34:37]
	v_mfma_f32_16x16x32_bf16 v[230:233], v[162:165], v[74:77], v[58:61]
	v_mfma_f32_16x16x32_bf16 v[234:237], v[162:165], v[90:93], v[50:53]
	v_mfma_f32_16x16x32_bf16 v[238:241], v[162:165], v[190:193], v[42:45]
	v_mfma_f32_16x16x32_bf16 v[130:133], v[162:165], v[202:205], v[34:37]
	v_mfma_f32_16x16x32_bf16 v[30:33], v[98:101], v[66:69], v[30:33]
	v_mfma_f32_16x16x32_bf16 v[22:25], v[98:101], v[82:85], v[22:25]
	v_mfma_f32_16x16x32_bf16 v[14:17], v[98:101], v[186:189], v[14:17]
	v_mfma_f32_16x16x32_bf16 v[6:9], v[98:101], v[198:201], v[6:9]
	v_mfma_f32_16x16x32_bf16 v[30:33], v[106:109], v[74:77], v[30:33]
	v_mfma_f32_16x16x32_bf16 v[26:29], v[114:117], v[66:69], v[26:29]
	v_mfma_f32_16x16x32_bf16 v[22:25], v[106:109], v[90:93], v[22:25]
	v_mfma_f32_16x16x32_bf16 v[18:21], v[114:117], v[82:85], v[18:21]
	v_mfma_f32_16x16x32_bf16 v[14:17], v[106:109], v[190:193], v[14:17]
	v_mfma_f32_16x16x32_bf16 v[10:13], v[114:117], v[186:189], v[10:13]
	v_mfma_f32_16x16x32_bf16 v[6:9], v[106:109], v[202:205], v[6:9]
	v_mfma_f32_16x16x32_bf16 v[2:5], v[114:117], v[198:201], v[2:5]
	v_mfma_f32_16x16x32_bf16 v[134:137], v[122:125], v[74:77], v[26:29]
	v_mfma_f32_16x16x32_bf16 v[150:153], v[122:125], v[90:93], v[18:21]
	v_mfma_f32_16x16x32_bf16 v[160:163], v[122:125], v[190:193], v[10:13]
	v_mfma_f32_16x16x32_bf16 v[186:189], v[122:125], v[202:205], v[2:5]
	s_barrier
	s_nop 1
	ds_read_b128 v[2:5], v148
	ds_read_b128 v[10:13], v148 offset:1024
	ds_read_b128 v[190:193], v148 offset:2048
	ds_read_b128 v[198:201], v148 offset:3072
	ds_read_b128 v[18:21], v146 offset:32768
	ds_read_b128 v[26:29], v146 offset:33792
	ds_read_b128 v[34:37], v145 offset:32768
	ds_read_b128 v[42:45], v145 offset:33792
	ds_read_b128 v[50:53], v144 offset:32768
	ds_read_b128 v[58:61], v144 offset:33792
	ds_read_b128 v[202:205], v143 offset:32768
	ds_read_b128 v[242:245], v143 offset:33792
	s_waitcnt vmcnt(2)
	s_barrier
	s_waitcnt lgkmcnt(0)
	s_waitcnt lgkmcnt(0)
	v_mfma_f32_16x16x32_bf16 v[66:69], v[2:5], v[18:21], v[126:129]
	v_mfma_f32_16x16x32_bf16 v[122:125], v[10:13], v[26:29], v[66:69]
	v_mfma_f32_16x16x32_bf16 v[66:69], v[190:193], v[18:21], v[156:159]
	v_mfma_f32_16x16x32_bf16 v[114:117], v[198:201], v[26:29], v[66:69]
	v_mfma_f32_16x16x32_bf16 v[66:69], v[2:5], v[34:37], v[118:121]
	v_mfma_f32_16x16x32_bf16 v[106:109], v[10:13], v[42:45], v[66:69]
	v_mfma_f32_16x16x32_bf16 v[66:69], v[190:193], v[34:37], v[218:221]
	v_mfma_f32_16x16x32_bf16 v[98:101], v[198:201], v[42:45], v[66:69]
	v_mfma_f32_16x16x32_bf16 v[66:69], v[2:5], v[50:53], v[110:113]
	v_mfma_f32_16x16x32_bf16 v[90:93], v[10:13], v[58:61], v[66:69]
	v_mfma_f32_16x16x32_bf16 v[66:69], v[190:193], v[50:53], v[222:225]
	v_mfma_f32_16x16x32_bf16 v[82:85], v[198:201], v[58:61], v[66:69]
	v_mfma_f32_16x16x32_bf16 v[66:69], v[2:5], v[202:205], v[102:105]
	v_mfma_f32_16x16x32_bf16 v[74:77], v[10:13], v[242:245], v[66:69]
	v_mfma_f32_16x16x32_bf16 v[66:69], v[190:193], v[202:205], v[226:229]
	v_mfma_f32_16x16x32_bf16 v[66:69], v[198:201], v[242:245], v[66:69]
	s_barrier
	ds_read_b128 v[154:157], v147
	ds_read_b128 v[218:221], v147 offset:1024
	ds_read_b128 v[222:225], v147 offset:2048
	ds_read_b128 v[226:229], v147 offset:3072
	s_waitcnt vmcnt(0)
	s_barrier
	s_waitcnt lgkmcnt(0)
	s_waitcnt lgkmcnt(0)
	v_mfma_f32_16x16x32_bf16 v[94:97], v[154:157], v[18:21], v[94:97]
	v_mfma_f32_16x16x32_bf16 v[18:21], v[222:225], v[18:21], v[166:169]
	v_mfma_f32_16x16x32_bf16 v[118:121], v[226:229], v[26:29], v[18:21]
	v_mfma_f32_16x16x32_bf16 v[18:21], v[154:157], v[34:37], v[86:89]
	v_mfma_f32_16x16x32_bf16 v[110:113], v[218:221], v[42:45], v[18:21]
	v_mfma_f32_16x16x32_bf16 v[18:21], v[222:225], v[34:37], v[170:173]
	v_mfma_f32_16x16x32_bf16 v[102:105], v[226:229], v[42:45], v[18:21]
	v_mfma_f32_16x16x32_bf16 v[18:21], v[154:157], v[50:53], v[78:81]
	v_mfma_f32_16x16x32_bf16 v[126:129], v[218:221], v[26:29], v[94:97]
	v_mfma_f32_16x16x32_bf16 v[94:97], v[218:221], v[58:61], v[18:21]
	v_mfma_f32_16x16x32_bf16 v[18:21], v[222:225], v[50:53], v[174:177]
	v_mfma_f32_16x16x32_bf16 v[86:89], v[226:229], v[58:61], v[18:21]
	v_mfma_f32_16x16x32_bf16 v[18:21], v[154:157], v[202:205], v[70:73]
	v_mfma_f32_16x16x32_bf16 v[78:81], v[218:221], v[242:245], v[18:21]
	v_mfma_f32_16x16x32_bf16 v[18:21], v[222:225], v[202:205], v[178:181]
	v_mfma_f32_16x16x32_bf16 v[70:73], v[226:229], v[242:245], v[18:21]
	s_barrier
	ds_read_b128 v[164:167], v146 offset:49152
	ds_read_b128 v[146:149], v146 offset:50176
	ds_read_b128 v[168:171], v145 offset:49152
	ds_read_b128 v[172:175], v145 offset:50176
	ds_read_b128 v[176:179], v144 offset:49152
	ds_read_b128 v[180:183], v144 offset:50176
	ds_read_b128 v[202:205], v143 offset:49152
	ds_read_b128 v[142:145], v143 offset:50176
	s_barrier
	s_waitcnt lgkmcnt(0)
	s_waitcnt lgkmcnt(0)
	v_mfma_f32_16x16x32_bf16 v[18:21], v[2:5], v[164:167], v[62:65]
	v_mfma_f32_16x16x32_bf16 v[58:61], v[10:13], v[146:149], v[18:21]
	v_mfma_f32_16x16x32_bf16 v[18:21], v[190:193], v[164:167], v[230:233]
	v_mfma_f32_16x16x32_bf16 v[50:53], v[198:201], v[146:149], v[18:21]
	v_mfma_f32_16x16x32_bf16 v[18:21], v[2:5], v[168:171], v[54:57]
	v_mfma_f32_16x16x32_bf16 v[42:45], v[10:13], v[172:175], v[18:21]
	v_mfma_f32_16x16x32_bf16 v[18:21], v[190:193], v[168:171], v[234:237]
	v_mfma_f32_16x16x32_bf16 v[34:37], v[198:201], v[172:175], v[18:21]
	v_mfma_f32_16x16x32_bf16 v[18:21], v[2:5], v[176:179], v[46:49]
	v_mfma_f32_16x16x32_bf16 v[2:5], v[2:5], v[202:205], v[38:41]
	v_mfma_f32_16x16x32_bf16 v[26:29], v[10:13], v[180:183], v[18:21]
	v_mfma_f32_16x16x32_bf16 v[18:21], v[190:193], v[176:179], v[238:241]
	v_mfma_f32_16x16x32_bf16 v[10:13], v[10:13], v[142:145], v[2:5]
	v_mfma_f32_16x16x32_bf16 v[2:5], v[190:193], v[202:205], v[130:133]
	v_mfma_f32_16x16x32_bf16 v[18:21], v[198:201], v[180:183], v[18:21]
	v_mfma_f32_16x16x32_bf16 v[2:5], v[198:201], v[142:145], v[2:5]
	v_mfma_f32_16x16x32_bf16 v[30:33], v[154:157], v[164:167], v[30:33]
	v_mfma_f32_16x16x32_bf16 v[62:65], v[218:221], v[146:149], v[30:33]
	v_mfma_f32_16x16x32_bf16 v[30:33], v[222:225], v[164:167], v[134:137]
	v_mfma_f32_16x16x32_bf16 v[22:25], v[154:157], v[168:171], v[22:25]
	v_mfma_f32_16x16x32_bf16 v[14:17], v[154:157], v[176:179], v[14:17]
	v_mfma_f32_16x16x32_bf16 v[54:57], v[226:229], v[146:149], v[30:33]
	v_mfma_f32_16x16x32_bf16 v[46:49], v[218:221], v[172:175], v[22:25]
	v_mfma_f32_16x16x32_bf16 v[22:25], v[222:225], v[168:171], v[150:153]
	v_mfma_f32_16x16x32_bf16 v[30:33], v[218:221], v[180:183], v[14:17]
	v_mfma_f32_16x16x32_bf16 v[14:17], v[222:225], v[176:179], v[160:163]
	v_mfma_f32_16x16x32_bf16 v[6:9], v[154:157], v[202:205], v[6:9]
	v_mfma_f32_16x16x32_bf16 v[38:41], v[226:229], v[172:175], v[22:25]
	v_mfma_f32_16x16x32_bf16 v[22:25], v[226:229], v[180:183], v[14:17]
	v_mfma_f32_16x16x32_bf16 v[14:17], v[218:221], v[142:145], v[6:9]
	v_mfma_f32_16x16x32_bf16 v[6:9], v[222:225], v[202:205], v[186:189]
	v_mfma_f32_16x16x32_bf16 v[6:9], v[226:229], v[142:145], v[6:9]
	s_movk_i32 s1, 0x100
	v_cmp_gt_u32_e32 vcc, s1, v140
	s_barrier
	s_and_saveexec_b64 s[2:3], vcc
	s_cbranch_execz .LBB0_926
	s_barrier
